# GEMM1 K-loop: per-segment s_setprio toggles removed
# speedup vs baseline: 1.0003x; 1.0003x over previous
.LBB0_188:
	ds_read_b128 v[130:133], v178
	ds_read_b128 v[134:137], v178 offset:1024
	ds_read_b128 v[138:141], v178 offset:2048
	ds_read_b128 v[142:145], v178 offset:3072
	s_add_u32 s15, s34, 0xfffc0080
	s_addc_u32 s16, s35, -1
	s_cmp_eq_u32 s14, 12
	s_cselect_b32 s39, s25, s16
	s_cselect_b32 s38, s31, s15
	s_cselect_b32 s37, s23, vcc_hi
	s_cselect_b32 s36, s90, vcc_lo
	v_lshl_add_u64 v[206:207], s[34:35], 0, v[164:165]
	s_add_i32 m0, s68, 0xc000
	ds_read_b128 v[146:149], v179
	ds_read_b128 v[174:177], v179 offset:1024
	ds_read_b128 v[182:185], v179 offset:2048
	ds_read_b128 v[186:189], v179 offset:3072
	ds_read_b128 v[190:193], v179 offset:4096
	ds_read_b128 v[194:197], v179 offset:5120
	ds_read_b128 v[198:201], v179 offset:6144
	ds_read_b128 v[202:205], v179 offset:7168
	global_load_lds_dwordx4 v[206:207], off
	v_lshl_add_u64 v[206:207], s[34:35], 0, v[166:167]
	s_add_i32 m0, s68, 0xe000
	s_nop 0
	global_load_lds_dwordx4 v[206:207], off
	s_waitcnt lgkmcnt(8)
	s_barrier
	s_waitcnt lgkmcnt(0)
	s_waitcnt lgkmcnt(0)
	v_mfma_f32_16x16x32_bf16 v[126:129], v[130:133], v[146:149], v[126:129]
	v_mfma_f32_16x16x32_bf16 v[122:125], v[138:141], v[146:149], v[122:125]
	v_mfma_f32_16x16x32_bf16 v[110:113], v[130:133], v[182:185], v[110:113]
	v_mfma_f32_16x16x32_bf16 v[106:109], v[138:141], v[182:185], v[106:109]
	v_mfma_f32_16x16x32_bf16 v[94:97], v[130:133], v[190:193], v[94:97]
	v_mfma_f32_16x16x32_bf16 v[90:93], v[138:141], v[190:193], v[90:93]
	v_mfma_f32_16x16x32_bf16 v[78:81], v[130:133], v[198:201], v[78:81]
	v_mfma_f32_16x16x32_bf16 v[74:77], v[138:141], v[198:201], v[74:77]
	v_mfma_f32_16x16x32_bf16 v[126:129], v[134:137], v[174:177], v[126:129]
	v_mfma_f32_16x16x32_bf16 v[122:125], v[142:145], v[174:177], v[122:125]
	v_mfma_f32_16x16x32_bf16 v[110:113], v[134:137], v[186:189], v[110:113]
	v_mfma_f32_16x16x32_bf16 v[106:109], v[142:145], v[186:189], v[106:109]
	v_mfma_f32_16x16x32_bf16 v[94:97], v[134:137], v[194:197], v[94:97]
	v_mfma_f32_16x16x32_bf16 v[90:93], v[142:145], v[194:197], v[90:93]
	v_mfma_f32_16x16x32_bf16 v[78:81], v[134:137], v[202:205], v[78:81]
	v_mfma_f32_16x16x32_bf16 v[74:77], v[142:145], v[202:205], v[74:77]
	s_barrier
	s_add_i32 s15, s13, s41
	v_lshl_add_u64 v[222:223], s[36:37], 0, v[152:153]
	s_mov_b32 m0, s15
	ds_read_b128 v[206:209], v180
	ds_read_b128 v[210:213], v180 offset:1024
	ds_read_b128 v[214:217], v180 offset:2048
	ds_read_b128 v[218:221], v180 offset:3072
	global_load_lds_dwordx4 v[222:223], off
	v_lshl_add_u64 v[224:225], s[36:37], 0, v[156:157]
	s_add_i32 m0, s15, 0x2000
	s_nop 0
	global_load_lds_dwordx4 v[224:225], off
	s_barrier
	s_waitcnt lgkmcnt(0)
	s_waitcnt lgkmcnt(0)
	v_mfma_f32_16x16x32_bf16 v[118:121], v[206:209], v[146:149], v[118:121]
	v_mfma_f32_16x16x32_bf16 v[114:117], v[214:217], v[146:149], v[114:117]
	v_mfma_f32_16x16x32_bf16 v[102:105], v[206:209], v[182:185], v[102:105]
	v_mfma_f32_16x16x32_bf16 v[98:101], v[214:217], v[182:185], v[98:101]
	v_mfma_f32_16x16x32_bf16 v[86:89], v[206:209], v[190:193], v[86:89]
	v_mfma_f32_16x16x32_bf16 v[82:85], v[214:217], v[190:193], v[82:85]
	v_mfma_f32_16x16x32_bf16 v[70:73], v[206:209], v[198:201], v[70:73]
	v_mfma_f32_16x16x32_bf16 v[66:69], v[214:217], v[198:201], v[66:69]
	v_mfma_f32_16x16x32_bf16 v[118:121], v[210:213], v[174:177], v[118:121]
	v_mfma_f32_16x16x32_bf16 v[114:117], v[218:221], v[174:177], v[114:117]
	v_mfma_f32_16x16x32_bf16 v[102:105], v[210:213], v[186:189], v[102:105]
	v_mfma_f32_16x16x32_bf16 v[98:101], v[218:221], v[186:189], v[98:101]
	v_mfma_f32_16x16x32_bf16 v[86:89], v[210:213], v[194:197], v[86:89]
	v_mfma_f32_16x16x32_bf16 v[82:85], v[218:221], v[194:197], v[82:85]
	v_mfma_f32_16x16x32_bf16 v[70:73], v[210:213], v[202:205], v[70:73]
	v_mfma_f32_16x16x32_bf16 v[66:69], v[218:221], v[202:205], v[66:69]
	s_mov_b32 m0, s68
	v_lshl_add_u64 v[226:227], s[38:39], 0, v[150:151]
	s_barrier
	ds_read_b128 v[146:149], v179 offset:16384
	ds_read_b128 v[174:177], v179 offset:17408
	ds_read_b128 v[182:185], v179 offset:18432
	ds_read_b128 v[186:189], v179 offset:19456
	ds_read_b128 v[190:193], v179 offset:20480
	ds_read_b128 v[194:197], v179 offset:21504
	ds_read_b128 v[198:201], v179 offset:22528
	ds_read_b128 v[202:205], v179 offset:23552
	global_load_lds_dwordx4 v[226:227], off
	v_lshl_add_u64 v[228:229], s[38:39], 0, v[154:155]
	s_mov_b32 m0, s69
	s_nop 0
	global_load_lds_dwordx4 v[228:229], off
	s_barrier
	s_waitcnt lgkmcnt(0)
	s_waitcnt lgkmcnt(0)
	v_mfma_f32_16x16x32_bf16 v[62:65], v[130:133], v[146:149], v[62:65]
	v_mfma_f32_16x16x32_bf16 v[58:61], v[138:141], v[146:149], v[58:61]
	v_mfma_f32_16x16x32_bf16 v[46:49], v[130:133], v[182:185], v[46:49]
	v_mfma_f32_16x16x32_bf16 v[42:45], v[138:141], v[182:185], v[42:45]
	v_mfma_f32_16x16x32_bf16 v[30:33], v[130:133], v[190:193], v[30:33]
	v_mfma_f32_16x16x32_bf16 v[26:29], v[138:141], v[190:193], v[26:29]
	v_mfma_f32_16x16x32_bf16 v[14:17], v[130:133], v[198:201], v[14:17]
	v_mfma_f32_16x16x32_bf16 v[10:13], v[138:141], v[198:201], v[10:13]
	v_mfma_f32_16x16x32_bf16 v[62:65], v[134:137], v[174:177], v[62:65]
	v_mfma_f32_16x16x32_bf16 v[58:61], v[142:145], v[174:177], v[58:61]
	v_mfma_f32_16x16x32_bf16 v[46:49], v[134:137], v[186:189], v[46:49]
	v_mfma_f32_16x16x32_bf16 v[42:45], v[142:145], v[186:189], v[42:45]
	v_mfma_f32_16x16x32_bf16 v[30:33], v[134:137], v[194:197], v[30:33]
	v_mfma_f32_16x16x32_bf16 v[26:29], v[142:145], v[194:197], v[26:29]
	v_mfma_f32_16x16x32_bf16 v[14:17], v[134:137], v[202:205], v[14:17]
	v_mfma_f32_16x16x32_bf16 v[10:13], v[142:145], v[202:205], v[10:13]
	s_barrier
	s_add_u32 s16, s36, 0x40000
	s_addc_u32 s17, s37, 0
	s_add_i32 s15, s88, s41
	v_lshl_add_u64 v[130:131], s[16:17], 0, v[152:153]
	s_mov_b32 m0, s15
	s_nop 0
	global_load_lds_dwordx4 v[130:131], off
	v_lshl_add_u64 v[130:131], s[16:17], 0, v[156:157]
	s_add_i32 m0, s15, 0x2000
	s_nop 0
	global_load_lds_dwordx4 v[130:131], off
	s_waitcnt vmcnt(6)
	s_barrier
	v_mfma_f32_16x16x32_bf16 v[54:57], v[206:209], v[146:149], v[54:57]
	v_mfma_f32_16x16x32_bf16 v[50:53], v[214:217], v[146:149], v[50:53]
	v_mfma_f32_16x16x32_bf16 v[38:41], v[206:209], v[182:185], v[38:41]
	v_mfma_f32_16x16x32_bf16 v[34:37], v[214:217], v[182:185], v[34:37]
	v_mfma_f32_16x16x32_bf16 v[22:25], v[206:209], v[190:193], v[22:25]
	v_mfma_f32_16x16x32_bf16 v[18:21], v[214:217], v[190:193], v[18:21]
	v_mfma_f32_16x16x32_bf16 v[6:9], v[206:209], v[198:201], v[6:9]
	v_mfma_f32_16x16x32_bf16 v[2:5], v[214:217], v[198:201], v[2:5]
	v_mfma_f32_16x16x32_bf16 v[54:57], v[210:213], v[174:177], v[54:57]
	v_mfma_f32_16x16x32_bf16 v[50:53], v[218:221], v[174:177], v[50:53]
	v_mfma_f32_16x16x32_bf16 v[38:41], v[210:213], v[186:189], v[38:41]
	v_mfma_f32_16x16x32_bf16 v[34:37], v[218:221], v[186:189], v[34:37]
	v_mfma_f32_16x16x32_bf16 v[22:25], v[210:213], v[194:197], v[22:25]
	v_mfma_f32_16x16x32_bf16 v[18:21], v[218:221], v[194:197], v[18:21]
	v_mfma_f32_16x16x32_bf16 v[6:9], v[210:213], v[202:205], v[6:9]
	v_mfma_f32_16x16x32_bf16 v[2:5], v[218:221], v[202:205], v[2:5]
	s_add_i32 s15, 0, 0x18000
	v_add_u32_e32 v142, s15, v161
	s_barrier
	ds_read_b128 v[130:133], v142
	ds_read_b128 v[134:137], v142 offset:1024
	ds_read_b128 v[138:141], v142 offset:2048
	ds_read_b128 v[142:145], v142 offset:3072
	s_add_u32 s16, s38, 0x40000
	s_addc_u32 s17, s39, 0
	s_mov_b32 m0, s84
	v_lshl_add_u64 v[206:207], s[16:17], 0, v[150:151]
	ds_read_b128 v[146:149], v179 offset:32768
	ds_read_b128 v[174:177], v179 offset:33792
	ds_read_b128 v[182:185], v179 offset:34816
	ds_read_b128 v[186:189], v179 offset:35840
	ds_read_b128 v[190:193], v179 offset:36864
	ds_read_b128 v[194:197], v179 offset:37888
	ds_read_b128 v[198:201], v179 offset:38912
	ds_read_b128 v[202:205], v179 offset:39936
	global_load_lds_dwordx4 v[206:207], off
	v_lshl_add_u64 v[206:207], s[16:17], 0, v[154:155]
	s_mov_b32 m0, s85
	s_nop 0
	global_load_lds_dwordx4 v[206:207], off
	s_waitcnt lgkmcnt(8)
	s_barrier
	s_waitcnt lgkmcnt(0)
	s_waitcnt lgkmcnt(0)
	v_mfma_f32_16x16x32_bf16 v[126:129], v[130:133], v[146:149], v[126:129]
	v_mfma_f32_16x16x32_bf16 v[122:125], v[138:141], v[146:149], v[122:125]
	v_mfma_f32_16x16x32_bf16 v[110:113], v[130:133], v[182:185], v[110:113]
	v_mfma_f32_16x16x32_bf16 v[106:109], v[138:141], v[182:185], v[106:109]
	v_mfma_f32_16x16x32_bf16 v[94:97], v[130:133], v[190:193], v[94:97]
	v_mfma_f32_16x16x32_bf16 v[90:93], v[138:141], v[190:193], v[90:93]
	v_mfma_f32_16x16x32_bf16 v[78:81], v[130:133], v[198:201], v[78:81]
	v_mfma_f32_16x16x32_bf16 v[74:77], v[138:141], v[198:201], v[74:77]
	v_mfma_f32_16x16x32_bf16 v[126:129], v[134:137], v[174:177], v[126:129]
	v_mfma_f32_16x16x32_bf16 v[122:125], v[142:145], v[174:177], v[122:125]
	v_mfma_f32_16x16x32_bf16 v[110:113], v[134:137], v[186:189], v[110:113]
	v_mfma_f32_16x16x32_bf16 v[106:109], v[142:145], v[186:189], v[106:109]
	v_mfma_f32_16x16x32_bf16 v[94:97], v[134:137], v[194:197], v[94:97]
	v_mfma_f32_16x16x32_bf16 v[90:93], v[142:145], v[194:197], v[90:93]
	v_mfma_f32_16x16x32_bf16 v[78:81], v[134:137], v[202:205], v[78:81]
	v_mfma_f32_16x16x32_bf16 v[74:77], v[142:145], v[202:205], v[74:77]
	s_barrier
	s_add_i32 s38, 0, 0x1c000
	s_add_i32 s15, s15, s41
	v_add_u32_e32 v158, s38, v161
	v_lshl_add_u64 v[222:223], v[222:223], 0, s[10:11]
	s_mov_b32 m0, s15
	ds_read_b128 v[206:209], v158
	ds_read_b128 v[210:213], v158 offset:1024
	ds_read_b128 v[214:217], v158 offset:2048
	ds_read_b128 v[218:221], v158 offset:3072
	global_load_lds_dwordx4 v[222:223], off
	v_lshl_add_u64 v[222:223], v[224:225], 0, s[10:11]
	s_add_i32 m0, s15, 0x2000
	s_nop 0
	global_load_lds_dwordx4 v[222:223], off
	s_barrier
	s_waitcnt lgkmcnt(0)
	s_waitcnt lgkmcnt(0)
	v_mfma_f32_16x16x32_bf16 v[118:121], v[206:209], v[146:149], v[118:121]
	v_mfma_f32_16x16x32_bf16 v[114:117], v[214:217], v[146:149], v[114:117]
	v_mfma_f32_16x16x32_bf16 v[102:105], v[206:209], v[182:185], v[102:105]
	v_mfma_f32_16x16x32_bf16 v[98:101], v[214:217], v[182:185], v[98:101]
	v_mfma_f32_16x16x32_bf16 v[86:89], v[206:209], v[190:193], v[86:89]
	v_mfma_f32_16x16x32_bf16 v[82:85], v[214:217], v[190:193], v[82:85]
	v_mfma_f32_16x16x32_bf16 v[70:73], v[206:209], v[198:201], v[70:73]
	v_mfma_f32_16x16x32_bf16 v[66:69], v[214:217], v[198:201], v[66:69]
	v_mfma_f32_16x16x32_bf16 v[118:121], v[210:213], v[174:177], v[118:121]
	v_mfma_f32_16x16x32_bf16 v[114:117], v[218:221], v[174:177], v[114:117]
	v_mfma_f32_16x16x32_bf16 v[102:105], v[210:213], v[186:189], v[102:105]
	v_mfma_f32_16x16x32_bf16 v[98:101], v[218:221], v[186:189], v[98:101]
	v_mfma_f32_16x16x32_bf16 v[86:89], v[210:213], v[194:197], v[86:89]
	v_mfma_f32_16x16x32_bf16 v[82:85], v[218:221], v[194:197], v[82:85]
	v_mfma_f32_16x16x32_bf16 v[70:73], v[210:213], v[202:205], v[70:73]
	v_mfma_f32_16x16x32_bf16 v[66:69], v[218:221], v[202:205], v[66:69]
	s_mov_b32 m0, s97
	v_lshl_add_u64 v[222:223], v[226:227], 0, s[10:11]
	s_barrier
	ds_read_b128 v[146:149], v179 offset:49152
	ds_read_b128 v[174:177], v179 offset:50176
	ds_read_b128 v[182:185], v179 offset:51200
	ds_read_b128 v[186:189], v179 offset:52224
	ds_read_b128 v[190:193], v179 offset:53248
	ds_read_b128 v[194:197], v179 offset:54272
	ds_read_b128 v[198:201], v179 offset:55296
	ds_read_b128 v[202:205], v179 offset:56320
	global_load_lds_dwordx4 v[222:223], off
	v_lshl_add_u64 v[222:223], v[228:229], 0, s[10:11]
	s_mov_b32 m0, s91
	s_nop 0
	global_load_lds_dwordx4 v[222:223], off
	s_barrier
	s_waitcnt lgkmcnt(0)
	s_waitcnt lgkmcnt(0)
	v_mfma_f32_16x16x32_bf16 v[62:65], v[130:133], v[146:149], v[62:65]
	v_mfma_f32_16x16x32_bf16 v[58:61], v[138:141], v[146:149], v[58:61]
	v_mfma_f32_16x16x32_bf16 v[46:49], v[130:133], v[182:185], v[46:49]
	v_mfma_f32_16x16x32_bf16 v[42:45], v[138:141], v[182:185], v[42:45]
	v_mfma_f32_16x16x32_bf16 v[30:33], v[130:133], v[190:193], v[30:33]
	v_mfma_f32_16x16x32_bf16 v[26:29], v[138:141], v[190:193], v[26:29]
	v_mfma_f32_16x16x32_bf16 v[14:17], v[130:133], v[198:201], v[14:17]
	v_mfma_f32_16x16x32_bf16 v[10:13], v[138:141], v[198:201], v[10:13]
	v_mfma_f32_16x16x32_bf16 v[62:65], v[134:137], v[174:177], v[62:65]
	v_mfma_f32_16x16x32_bf16 v[58:61], v[142:145], v[174:177], v[58:61]
	v_mfma_f32_16x16x32_bf16 v[46:49], v[134:137], v[186:189], v[46:49]
	v_mfma_f32_16x16x32_bf16 v[42:45], v[142:145], v[186:189], v[42:45]
	v_mfma_f32_16x16x32_bf16 v[30:33], v[134:137], v[194:197], v[30:33]
	v_mfma_f32_16x16x32_bf16 v[26:29], v[142:145], v[194:197], v[26:29]
	v_mfma_f32_16x16x32_bf16 v[14:17], v[134:137], v[202:205], v[14:17]
	v_mfma_f32_16x16x32_bf16 v[10:13], v[142:145], v[202:205], v[10:13]
	s_barrier
	s_add_u32 s16, s36, 0x40080
	s_addc_u32 s17, s37, 0
	s_add_i32 s15, s38, s41
	v_lshl_add_u64 v[130:131], s[16:17], 0, v[152:153]
	s_mov_b32 m0, s15
	s_nop 0
	global_load_lds_dwordx4 v[130:131], off
	v_lshl_add_u64 v[130:131], s[16:17], 0, v[156:157]
	s_add_i32 m0, s15, 0x2000
	s_nop 0
	global_load_lds_dwordx4 v[130:131], off
	s_waitcnt vmcnt(6)
	s_barrier
	v_mfma_f32_16x16x32_bf16 v[54:57], v[206:209], v[146:149], v[54:57]
	v_mfma_f32_16x16x32_bf16 v[50:53], v[214:217], v[146:149], v[50:53]
	v_mfma_f32_16x16x32_bf16 v[38:41], v[206:209], v[182:185], v[38:41]
	v_mfma_f32_16x16x32_bf16 v[34:37], v[214:217], v[182:185], v[34:37]
	v_mfma_f32_16x16x32_bf16 v[22:25], v[206:209], v[190:193], v[22:25]
	v_mfma_f32_16x16x32_bf16 v[18:21], v[214:217], v[190:193], v[18:21]
	v_mfma_f32_16x16x32_bf16 v[6:9], v[206:209], v[198:201], v[6:9]
	v_mfma_f32_16x16x32_bf16 v[2:5], v[214:217], v[198:201], v[2:5]
	v_mfma_f32_16x16x32_bf16 v[54:57], v[210:213], v[174:177], v[54:57]
	v_mfma_f32_16x16x32_bf16 v[50:53], v[218:221], v[174:177], v[50:53]
	v_mfma_f32_16x16x32_bf16 v[38:41], v[210:213], v[186:189], v[38:41]
	v_mfma_f32_16x16x32_bf16 v[34:37], v[218:221], v[186:189], v[34:37]
	v_mfma_f32_16x16x32_bf16 v[22:25], v[210:213], v[194:197], v[22:25]
	v_mfma_f32_16x16x32_bf16 v[18:21], v[218:221], v[194:197], v[18:21]
	v_mfma_f32_16x16x32_bf16 v[6:9], v[210:213], v[202:205], v[6:9]
	v_mfma_f32_16x16x32_bf16 v[2:5], v[218:221], v[202:205], v[2:5]
	s_add_i32 s14, s14, 2
	s_add_u32 s34, s34, 0x100
	s_addc_u32 s35, s35, 0
	s_add_u32 vcc_lo, vcc_lo, 0x100
	s_addc_u32 vcc_hi, vcc_hi, 0
	s_cmp_gt_u32 s14, 13
	s_barrier
	s_cbranch_scc0 .LBB0_188
	v_lshl_add_u32 v174, s30, 8, v1
	s_cmp_gt_i32 s12, 3
	s_mov_b64 s[34:35], -1
	s_cbranch_scc0 .LBB0_204
	s_cmp_gt_u32 s12, 7
	s_cbranch_scc0 .LBB0_201
	s_cmp_lt_u32 s12, 16
	s_cbranch_scc0 .LBB0_193
	s_add_i32 s14, s12, -8
	v_lshl_or_b32 v158, s14, 8, v160
	v_lshl_add_u64 v[134:135], v[158:159], 2, s[70:71]
	global_load_dwordx4 v[138:141], v[134:135], off offset:16
	global_load_dwordx4 v[142:145], v[134:135], off
	global_load_dwordx4 v[130:133], v[134:135], off offset:528
	s_nop 0
	global_load_dwordx4 v[134:137], v[134:135], off offset:512
	s_lshl_b32 s15, s30, 3
	s_add_i32 s14, s15, s14
	s_ashr_i32 s15, s14, 31
	s_lshl_b64 s[14:15], s[14:15], 17
	v_readlane_b32 s16, v254, 9
	s_add_u32 s30, s16, s14
	v_readlane_b32 s14, v254, 10
	s_addc_u32 s31, s14, s15
	v_mov_b32_e32 v173, v159
	v_lshl_add_u64 v[176:177], s[30:31], 0, v[172:173]
	s_movk_i32 s14, 0x1000
	s_mov_b64 s[34:35], 0
	s_waitcnt vmcnt(0)
	v_add_f32_e32 v149, v123, v139
	v_add_f32_e32 v146, v126, v142
	v_add_f32_e32 v147, v127, v143
	v_mul_f32_e32 v146, 0xbfb8aa3b, v146
	v_mul_f32_e32 v147, 0xbfb8aa3b, v147
	v_exp_f32_e32 v146, v146
	v_exp_f32_e32 v147, v147
	v_add_f32_e32 v148, v129, v145
	v_mul_f32_e32 v148, 0xbfb8aa3b, v148
	v_add_f32_e32 v146, 1.0, v146
	v_add_f32_e32 v147, 1.0, v147
	v_rcp_f32_e32 v146, v146
	v_rcp_f32_e32 v147, v147
	v_exp_f32_e32 v148, v148
	v_mul_f32_e32 v149, 0xbfb8aa3b, v149
	v_exp_f32_e32 v149, v149
	v_cvt_pk_bf16_f32 v146, v146, v147
	v_add_f32_e32 v147, v128, v144
	v_mul_f32_e32 v147, 0xbfb8aa3b, v147
	v_exp_f32_e32 v147, v147
	v_add_f32_e32 v148, 1.0, v148
	v_rcp_f32_e32 v148, v148
	v_add_f32_e32 v149, 1.0, v149
	v_add_f32_e32 v147, 1.0, v147
	v_rcp_f32_e32 v147, v147
	v_rcp_f32_e32 v149, v149
	v_add_f32_e32 v158, v125, v141
	v_mul_f32_e32 v158, 0xbfb8aa3b, v158
	v_cvt_pk_bf16_f32 v147, v147, v148
	v_add_f32_e32 v148, v122, v138
	v_mul_f32_e32 v148, 0xbfb8aa3b, v148
	v_exp_f32_e32 v148, v148
	v_exp_f32_e32 v158, v158
	v_add_f32_e32 v173, v87, v135
	v_mul_f32_e32 v173, 0xbfb8aa3b, v173
	v_add_f32_e32 v148, 1.0, v148
	v_rcp_f32_e32 v148, v148
	v_add_f32_e32 v158, 1.0, v158
	v_rcp_f32_e32 v158, v158
	v_exp_f32_e32 v173, v173
	v_cvt_pk_bf16_f32 v148, v148, v149
	v_add_f32_e32 v149, v124, v140
	v_mul_f32_e32 v149, 0xbfb8aa3b, v149
	v_exp_f32_e32 v149, v149
	v_add_f32_e32 v173, 1.0, v173
	v_rcp_f32_e32 v173, v173
	v_add_f32_e32 v149, 1.0, v149
	v_rcp_f32_e32 v149, v149
	s_nop 0
	v_cvt_pk_bf16_f32 v149, v149, v158
	global_store_dwordx4 v172, v[146:149], s[30:31]
	v_add_f32_e32 v158, v117, v133
	v_mul_f32_e32 v158, 0xbfb8aa3b, v158
	v_add_f32_e32 v146, v118, v134
	v_add_f32_e32 v147, v119, v135
	v_mul_f32_e32 v146, 0xbfb8aa3b, v146
	v_mul_f32_e32 v147, 0xbfb8aa3b, v147
	v_exp_f32_e32 v146, v146
	v_exp_f32_e32 v147, v147
	v_add_f32_e32 v148, v121, v137
	v_mul_f32_e32 v148, 0xbfb8aa3b, v148
	v_add_f32_e32 v146, 1.0, v146
	v_add_f32_e32 v147, 1.0, v147
	v_rcp_f32_e32 v146, v146
	v_rcp_f32_e32 v147, v147
	v_exp_f32_e32 v148, v148
	v_add_f32_e32 v149, v115, v131
	v_mul_f32_e32 v149, 0xbfb8aa3b, v149
	v_cvt_pk_bf16_f32 v146, v146, v147
	v_add_f32_e32 v147, v120, v136
	v_mul_f32_e32 v147, 0xbfb8aa3b, v147
	v_exp_f32_e32 v147, v147
	v_add_f32_e32 v148, 1.0, v148
	v_rcp_f32_e32 v148, v148
	v_exp_f32_e32 v149, v149
	v_add_f32_e32 v147, 1.0, v147
	v_rcp_f32_e32 v147, v147
	v_exp_f32_e32 v158, v158
	v_add_f32_e32 v149, 1.0, v149
	v_rcp_f32_e32 v149, v149
	v_cvt_pk_bf16_f32 v147, v147, v148
	v_add_f32_e32 v148, v114, v130
	v_mul_f32_e32 v148, 0xbfb8aa3b, v148
	v_exp_f32_e32 v148, v148
	v_add_f32_e32 v158, 1.0, v158
	v_rcp_f32_e32 v158, v158
	v_add_f32_e32 v148, 1.0, v148
	v_rcp_f32_e32 v148, v148
	s_nop 0
	v_cvt_pk_bf16_f32 v148, v148, v149
	v_add_f32_e32 v149, v116, v132
	v_mul_f32_e32 v149, 0xbfb8aa3b, v149
	v_exp_f32_e32 v149, v149
	s_nop 0
	v_add_f32_e32 v149, 1.0, v149
	v_rcp_f32_e32 v149, v149
	s_nop 0
	v_cvt_pk_bf16_f32 v149, v149, v158
	global_store_dwordx4 v172, v[146:149], s[30:31] offset:1024
	v_add_f32_e32 v158, v109, v141
	v_mul_f32_e32 v158, 0xbfb8aa3b, v158
	v_add_f32_e32 v146, v110, v142
	v_add_f32_e32 v147, v111, v143
	v_mul_f32_e32 v146, 0xbfb8aa3b, v146
	v_mul_f32_e32 v147, 0xbfb8aa3b, v147
	v_exp_f32_e32 v146, v146
	v_exp_f32_e32 v147, v147
	v_add_f32_e32 v148, v113, v145
	v_mul_f32_e32 v148, 0xbfb8aa3b, v148
	v_add_f32_e32 v146, 1.0, v146
	v_add_f32_e32 v147, 1.0, v147
	v_rcp_f32_e32 v146, v146
	v_rcp_f32_e32 v147, v147
	v_exp_f32_e32 v148, v148
	v_add_f32_e32 v149, v107, v139
	v_mul_f32_e32 v149, 0xbfb8aa3b, v149
	v_cvt_pk_bf16_f32 v146, v146, v147
	v_add_f32_e32 v147, v112, v144
	v_mul_f32_e32 v147, 0xbfb8aa3b, v147
	v_exp_f32_e32 v147, v147
	v_add_f32_e32 v148, 1.0, v148
	v_rcp_f32_e32 v148, v148
	v_exp_f32_e32 v149, v149
	v_add_f32_e32 v147, 1.0, v147
	v_rcp_f32_e32 v147, v147
	v_exp_f32_e32 v158, v158
	v_add_f32_e32 v149, 1.0, v149
	v_rcp_f32_e32 v149, v149
	v_cvt_pk_bf16_f32 v147, v147, v148
	v_add_f32_e32 v148, v106, v138
	v_mul_f32_e32 v148, 0xbfb8aa3b, v148
	v_exp_f32_e32 v148, v148
	v_add_f32_e32 v158, 1.0, v158
	v_rcp_f32_e32 v158, v158
	v_add_f32_e32 v148, 1.0, v148
	v_rcp_f32_e32 v148, v148
	s_nop 0
	v_cvt_pk_bf16_f32 v148, v148, v149
	v_add_f32_e32 v149, v108, v140
	v_mul_f32_e32 v149, 0xbfb8aa3b, v149
	v_exp_f32_e32 v149, v149
	s_nop 0
	v_add_f32_e32 v149, 1.0, v149
	v_rcp_f32_e32 v149, v149
	s_nop 0
	v_cvt_pk_bf16_f32 v149, v149, v158
	global_store_dwordx4 v172, v[146:149], s[30:31] offset:2048
	v_add_f32_e32 v158, v101, v133
	v_mul_f32_e32 v158, 0xbfb8aa3b, v158
	v_add_f32_e32 v146, v102, v134
	v_add_f32_e32 v147, v103, v135
	v_mul_f32_e32 v146, 0xbfb8aa3b, v146
	v_mul_f32_e32 v147, 0xbfb8aa3b, v147
	v_exp_f32_e32 v146, v146
	v_exp_f32_e32 v147, v147
	v_add_f32_e32 v148, v105, v137
	v_mul_f32_e32 v148, 0xbfb8aa3b, v148
	v_add_f32_e32 v146, 1.0, v146
	v_add_f32_e32 v147, 1.0, v147
	v_rcp_f32_e32 v146, v146
	v_rcp_f32_e32 v147, v147
	v_exp_f32_e32 v148, v148
	v_add_f32_e32 v149, v99, v131
	v_mul_f32_e32 v149, 0xbfb8aa3b, v149
	v_cvt_pk_bf16_f32 v146, v146, v147
	v_add_f32_e32 v147, v104, v136
	v_mul_f32_e32 v147, 0xbfb8aa3b, v147
	v_exp_f32_e32 v147, v147
	v_add_f32_e32 v148, 1.0, v148
	v_rcp_f32_e32 v148, v148
	v_exp_f32_e32 v149, v149
	v_add_f32_e32 v147, 1.0, v147
	v_rcp_f32_e32 v147, v147
	v_exp_f32_e32 v158, v158
	v_add_f32_e32 v149, 1.0, v149
	v_rcp_f32_e32 v149, v149
	v_cvt_pk_bf16_f32 v147, v147, v148
	v_add_f32_e32 v148, v98, v130
	v_mul_f32_e32 v148, 0xbfb8aa3b, v148
	v_exp_f32_e32 v148, v148
	v_add_f32_e32 v158, 1.0, v158
	v_rcp_f32_e32 v158, v158
	v_add_f32_e32 v148, 1.0, v148
	v_rcp_f32_e32 v148, v148
	s_nop 0
	v_cvt_pk_bf16_f32 v148, v148, v149
	v_add_f32_e32 v149, v100, v132
	v_mul_f32_e32 v149, 0xbfb8aa3b, v149
	v_exp_f32_e32 v149, v149
	s_nop 0
	v_add_f32_e32 v149, 1.0, v149
	v_rcp_f32_e32 v149, v149
	s_nop 0
	v_cvt_pk_bf16_f32 v149, v149, v158
	global_store_dwordx4 v172, v[146:149], s[30:31] offset:3072
	v_add_f32_e32 v158, v86, v134
	v_mul_f32_e32 v158, 0xbfb8aa3b, v158
	v_add_f32_e32 v146, v94, v142
	v_add_f32_e32 v147, v95, v143
	v_mul_f32_e32 v146, 0xbfb8aa3b, v146
	v_mul_f32_e32 v147, 0xbfb8aa3b, v147
	v_exp_f32_e32 v146, v146
	v_exp_f32_e32 v147, v147
	v_exp_f32_e32 v158, v158
	v_add_co_u32_e32 v148, vcc, s14, v176
	v_add_f32_e32 v146, 1.0, v146
	v_add_f32_e32 v147, 1.0, v147
	v_rcp_f32_e32 v146, v146
	v_rcp_f32_e32 v147, v147
	v_add_f32_e32 v158, 1.0, v158
	v_rcp_f32_e32 v158, v158
	v_addc_co_u32_e32 v149, vcc, 0, v177, vcc
	v_cvt_pk_bf16_f32 v182, v146, v147
	v_add_f32_e32 v146, v96, v144
	v_add_f32_e32 v147, v97, v145
	v_mul_f32_e32 v146, 0xbfb8aa3b, v146
	v_mul_f32_e32 v147, 0xbfb8aa3b, v147
	v_exp_f32_e32 v146, v146
	v_exp_f32_e32 v147, v147
	s_movk_i32 s14, 0x2000
	v_add_f32_e32 v146, 1.0, v146
	v_add_f32_e32 v147, 1.0, v147
	v_rcp_f32_e32 v146, v146
	v_rcp_f32_e32 v147, v147
	s_nop 0
	v_cvt_pk_bf16_f32 v183, v146, v147
	v_add_f32_e32 v146, v90, v138
	v_add_f32_e32 v147, v91, v139
	v_mul_f32_e32 v146, 0xbfb8aa3b, v146
	v_mul_f32_e32 v147, 0xbfb8aa3b, v147
	v_exp_f32_e32 v146, v146
	v_exp_f32_e32 v147, v147
	v_add_f32_e32 v146, 1.0, v146
	v_add_f32_e32 v147, 1.0, v147
	v_rcp_f32_e32 v146, v146
	v_rcp_f32_e32 v147, v147
	s_nop 0
	v_cvt_pk_bf16_f32 v184, v146, v147
	v_add_f32_e32 v146, v92, v140
	v_add_f32_e32 v147, v93, v141
	v_mul_f32_e32 v146, 0xbfb8aa3b, v146
	v_mul_f32_e32 v147, 0xbfb8aa3b, v147
	v_exp_f32_e32 v146, v146
	v_exp_f32_e32 v147, v147
	v_add_f32_e32 v146, 1.0, v146
	v_add_f32_e32 v147, 1.0, v147
	v_rcp_f32_e32 v146, v146
	v_rcp_f32_e32 v147, v147
	s_nop 0
	v_cvt_pk_bf16_f32 v185, v146, v147
	v_add_co_u32_e32 v146, vcc, s14, v176
	s_movk_i32 s14, 0x3000
	s_nop 0
	v_addc_co_u32_e32 v147, vcc, 0, v177, vcc
	global_store_dwordx4 v[146:147], v[182:185], off offset:-4096
	s_nop 1
	v_cvt_pk_bf16_f32 v182, v158, v173
	v_add_f32_e32 v158, v88, v136
	v_add_f32_e32 v173, v89, v137
	v_mul_f32_e32 v158, 0xbfb8aa3b, v158
	v_mul_f32_e32 v173, 0xbfb8aa3b, v173
	v_exp_f32_e32 v158, v158
	v_exp_f32_e32 v173, v173
	v_add_f32_e32 v158, 1.0, v158
	v_add_f32_e32 v173, 1.0, v173
	v_rcp_f32_e32 v158, v158
	v_rcp_f32_e32 v173, v173
	s_nop 0
	v_cvt_pk_bf16_f32 v183, v158, v173
	v_add_f32_e32 v158, v82, v130
	v_add_f32_e32 v173, v83, v131
	v_mul_f32_e32 v158, 0xbfb8aa3b, v158
	v_mul_f32_e32 v173, 0xbfb8aa3b, v173
	v_exp_f32_e32 v158, v158
	v_exp_f32_e32 v173, v173
	v_add_f32_e32 v158, 1.0, v158
	v_add_f32_e32 v173, 1.0, v173
	v_rcp_f32_e32 v158, v158
	v_rcp_f32_e32 v173, v173
	s_nop 0
	v_cvt_pk_bf16_f32 v184, v158, v173
	v_add_f32_e32 v158, v84, v132
	v_add_f32_e32 v173, v85, v133
	v_mul_f32_e32 v158, 0xbfb8aa3b, v158
	v_mul_f32_e32 v173, 0xbfb8aa3b, v173
	v_exp_f32_e32 v158, v158
	v_exp_f32_e32 v173, v173
	v_add_f32_e32 v158, 1.0, v158
	v_add_f32_e32 v173, 1.0, v173
	v_rcp_f32_e32 v158, v158
	v_rcp_f32_e32 v173, v173
	s_nop 0
	v_cvt_pk_bf16_f32 v185, v158, v173
	v_add_f32_e32 v158, v78, v142
	v_add_f32_e32 v173, v79, v143
	v_mul_f32_e32 v158, 0xbfb8aa3b, v158
	v_mul_f32_e32 v173, 0xbfb8aa3b, v173
	v_exp_f32_e32 v158, v158
	v_exp_f32_e32 v173, v173
	global_store_dwordx4 v[148:149], v[182:185], off offset:1024
	v_add_f32_e32 v158, 1.0, v158
	v_add_f32_e32 v173, 1.0, v173
	v_rcp_f32_e32 v158, v158
	v_rcp_f32_e32 v173, v173
	s_nop 0
	v_cvt_pk_bf16_f32 v182, v158, v173
	v_add_f32_e32 v158, v80, v144
	v_add_f32_e32 v173, v81, v145
	v_mul_f32_e32 v158, 0xbfb8aa3b, v158
	v_mul_f32_e32 v173, 0xbfb8aa3b, v173
	v_exp_f32_e32 v158, v158
	v_exp_f32_e32 v173, v173
	v_add_f32_e32 v158, 1.0, v158
	v_add_f32_e32 v173, 1.0, v173
	v_rcp_f32_e32 v158, v158
	v_rcp_f32_e32 v173, v173
	s_nop 0
	v_cvt_pk_bf16_f32 v183, v158, v173
	v_add_f32_e32 v158, v74, v138
	v_add_f32_e32 v173, v75, v139
	v_mul_f32_e32 v158, 0xbfb8aa3b, v158
	v_mul_f32_e32 v173, 0xbfb8aa3b, v173
	v_exp_f32_e32 v158, v158
	v_exp_f32_e32 v173, v173
	v_add_f32_e32 v158, 1.0, v158
	v_add_f32_e32 v173, 1.0, v173
	v_rcp_f32_e32 v158, v158
	v_rcp_f32_e32 v173, v173
	s_nop 0
	v_cvt_pk_bf16_f32 v184, v158, v173
	v_add_f32_e32 v158, v76, v140
	v_add_f32_e32 v173, v77, v141
	v_mul_f32_e32 v158, 0xbfb8aa3b, v158
	v_mul_f32_e32 v173, 0xbfb8aa3b, v173
	v_exp_f32_e32 v158, v158
	v_exp_f32_e32 v173, v173
	v_add_f32_e32 v158, 1.0, v158
	v_add_f32_e32 v173, 1.0, v173
	v_rcp_f32_e32 v158, v158
	v_rcp_f32_e32 v173, v173
	s_nop 0
	v_cvt_pk_bf16_f32 v185, v158, v173
	v_add_f32_e32 v158, v70, v134
	v_add_f32_e32 v173, v71, v135
	v_mul_f32_e32 v158, 0xbfb8aa3b, v158
	v_mul_f32_e32 v173, 0xbfb8aa3b, v173
	v_exp_f32_e32 v158, v158
	v_exp_f32_e32 v173, v173
	global_store_dwordx4 v[148:149], v[182:185], off offset:2048
	v_add_f32_e32 v158, 1.0, v158
	v_add_f32_e32 v173, 1.0, v173
	v_rcp_f32_e32 v158, v158
	v_rcp_f32_e32 v173, v173
	s_nop 0
	v_cvt_pk_bf16_f32 v182, v158, v173
	v_add_f32_e32 v158, v72, v136
	v_add_f32_e32 v173, v73, v137
	v_mul_f32_e32 v158, 0xbfb8aa3b, v158
	v_mul_f32_e32 v173, 0xbfb8aa3b, v173
	v_exp_f32_e32 v158, v158
	v_exp_f32_e32 v173, v173
	v_add_f32_e32 v158, 1.0, v158
	v_add_f32_e32 v173, 1.0, v173
	v_rcp_f32_e32 v158, v158
	v_rcp_f32_e32 v173, v173
	s_nop 0
	v_cvt_pk_bf16_f32 v183, v158, v173
	v_add_f32_e32 v158, v66, v130
	v_add_f32_e32 v173, v67, v131
	v_mul_f32_e32 v158, 0xbfb8aa3b, v158
	v_mul_f32_e32 v173, 0xbfb8aa3b, v173
	v_exp_f32_e32 v158, v158
	v_exp_f32_e32 v173, v173
	v_add_f32_e32 v158, 1.0, v158
	v_add_f32_e32 v173, 1.0, v173
	v_rcp_f32_e32 v158, v158
	v_rcp_f32_e32 v173, v173
	s_nop 0
	v_cvt_pk_bf16_f32 v184, v158, v173
	v_add_f32_e32 v158, v68, v132
	v_add_f32_e32 v173, v69, v133
	v_mul_f32_e32 v158, 0xbfb8aa3b, v158
	v_mul_f32_e32 v173, 0xbfb8aa3b, v173
	v_exp_f32_e32 v158, v158
	v_exp_f32_e32 v173, v173
	v_add_f32_e32 v158, 1.0, v158
	v_add_f32_e32 v173, 1.0, v173
	v_rcp_f32_e32 v158, v158
	v_rcp_f32_e32 v173, v173
	s_nop 0
	v_cvt_pk_bf16_f32 v185, v158, v173
	global_store_dwordx4 v[148:149], v[182:185], off offset:3072
	v_add_f32_e32 v148, v62, v142
	v_add_f32_e32 v149, v63, v143
	v_mul_f32_e32 v148, 0xbfb8aa3b, v148
	v_mul_f32_e32 v149, 0xbfb8aa3b, v149
	v_exp_f32_e32 v148, v148
	v_exp_f32_e32 v149, v149
	v_add_f32_e32 v148, 1.0, v148
	v_add_f32_e32 v149, 1.0, v149
	v_rcp_f32_e32 v148, v148
	v_rcp_f32_e32 v149, v149
	s_nop 0
	v_cvt_pk_bf16_f32 v182, v148, v149
	v_add_f32_e32 v148, v64, v144
	v_add_f32_e32 v149, v65, v145
	v_mul_f32_e32 v148, 0xbfb8aa3b, v148
	v_mul_f32_e32 v149, 0xbfb8aa3b, v149
	v_exp_f32_e32 v148, v148
	v_exp_f32_e32 v149, v149
	v_add_f32_e32 v148, 1.0, v148
	v_add_f32_e32 v149, 1.0, v149
	v_rcp_f32_e32 v148, v148
	v_rcp_f32_e32 v149, v149
	s_nop 0
	v_cvt_pk_bf16_f32 v183, v148, v149
	v_add_f32_e32 v148, v58, v138
	v_add_f32_e32 v149, v59, v139
	v_mul_f32_e32 v148, 0xbfb8aa3b, v148
	v_mul_f32_e32 v149, 0xbfb8aa3b, v149
	v_exp_f32_e32 v148, v148
	v_exp_f32_e32 v149, v149
	v_add_f32_e32 v148, 1.0, v148
	v_add_f32_e32 v149, 1.0, v149
	v_rcp_f32_e32 v148, v148
	v_rcp_f32_e32 v149, v149
	s_nop 0
	v_cvt_pk_bf16_f32 v184, v148, v149
	v_add_f32_e32 v148, v60, v140
	v_add_f32_e32 v149, v61, v141
	v_mul_f32_e32 v148, 0xbfb8aa3b, v148
	v_mul_f32_e32 v149, 0xbfb8aa3b, v149
	v_exp_f32_e32 v148, v148
	v_exp_f32_e32 v149, v149
	v_add_f32_e32 v148, 1.0, v148
	v_add_f32_e32 v149, 1.0, v149
	v_rcp_f32_e32 v148, v148
	v_rcp_f32_e32 v149, v149
	s_nop 0
	v_cvt_pk_bf16_f32 v185, v148, v149
	v_add_f32_e32 v148, v54, v134
	v_add_f32_e32 v149, v55, v135
	v_mul_f32_e32 v148, 0xbfb8aa3b, v148
	v_mul_f32_e32 v149, 0xbfb8aa3b, v149
	v_exp_f32_e32 v148, v148
	v_exp_f32_e32 v149, v149
	global_store_dwordx4 v[146:147], v[182:185], off
	v_add_f32_e32 v148, 1.0, v148
	v_add_f32_e32 v149, 1.0, v149
	v_rcp_f32_e32 v148, v148
	v_rcp_f32_e32 v149, v149
	s_nop 0
	v_cvt_pk_bf16_f32 v182, v148, v149
	v_add_f32_e32 v148, v56, v136
	v_add_f32_e32 v149, v57, v137
	v_mul_f32_e32 v148, 0xbfb8aa3b, v148
	v_mul_f32_e32 v149, 0xbfb8aa3b, v149
	v_exp_f32_e32 v148, v148
	v_exp_f32_e32 v149, v149
	v_add_f32_e32 v148, 1.0, v148
	v_add_f32_e32 v149, 1.0, v149
	v_rcp_f32_e32 v148, v148
	v_rcp_f32_e32 v149, v149
	s_nop 0
	v_cvt_pk_bf16_f32 v183, v148, v149
	v_add_f32_e32 v148, v50, v130
	v_add_f32_e32 v149, v51, v131
	v_mul_f32_e32 v148, 0xbfb8aa3b, v148
	v_mul_f32_e32 v149, 0xbfb8aa3b, v149
	v_exp_f32_e32 v148, v148
	v_exp_f32_e32 v149, v149
	v_add_f32_e32 v148, 1.0, v148
	v_add_f32_e32 v149, 1.0, v149
	v_rcp_f32_e32 v148, v148
	v_rcp_f32_e32 v149, v149
	s_nop 0
	v_cvt_pk_bf16_f32 v184, v148, v149
	v_add_f32_e32 v148, v52, v132
	v_add_f32_e32 v149, v53, v133
	v_mul_f32_e32 v148, 0xbfb8aa3b, v148
	v_mul_f32_e32 v149, 0xbfb8aa3b, v149
	v_exp_f32_e32 v148, v148
	v_exp_f32_e32 v149, v149
	v_add_f32_e32 v148, 1.0, v148
	v_add_f32_e32 v149, 1.0, v149
	v_rcp_f32_e32 v148, v148
	v_rcp_f32_e32 v149, v149
	s_nop 0
	v_cvt_pk_bf16_f32 v185, v148, v149
	v_add_f32_e32 v148, v46, v142
	v_add_f32_e32 v149, v47, v143
	v_mul_f32_e32 v148, 0xbfb8aa3b, v148
	v_mul_f32_e32 v149, 0xbfb8aa3b, v149
	v_exp_f32_e32 v148, v148
	v_exp_f32_e32 v149, v149
	global_store_dwordx4 v[146:147], v[182:185], off offset:1024
	v_add_f32_e32 v148, 1.0, v148
	v_add_f32_e32 v149, 1.0, v149
	v_rcp_f32_e32 v148, v148
	v_rcp_f32_e32 v149, v149
	s_nop 0
	v_cvt_pk_bf16_f32 v182, v148, v149
	v_add_f32_e32 v148, v48, v144
	v_add_f32_e32 v149, v49, v145
	v_mul_f32_e32 v148, 0xbfb8aa3b, v148
	v_mul_f32_e32 v149, 0xbfb8aa3b, v149
	v_exp_f32_e32 v148, v148
	v_exp_f32_e32 v149, v149
	v_add_f32_e32 v148, 1.0, v148
	v_add_f32_e32 v149, 1.0, v149
	v_rcp_f32_e32 v148, v148
	v_rcp_f32_e32 v149, v149
	s_nop 0
	v_cvt_pk_bf16_f32 v183, v148, v149
	v_add_f32_e32 v148, v42, v138
	v_add_f32_e32 v149, v43, v139
	v_mul_f32_e32 v148, 0xbfb8aa3b, v148
	v_mul_f32_e32 v149, 0xbfb8aa3b, v149
	v_exp_f32_e32 v148, v148
	v_exp_f32_e32 v149, v149
	v_add_f32_e32 v148, 1.0, v148
	v_add_f32_e32 v149, 1.0, v149
	v_rcp_f32_e32 v148, v148
	v_rcp_f32_e32 v149, v149
	s_nop 0
	v_cvt_pk_bf16_f32 v184, v148, v149
	v_add_f32_e32 v148, v44, v140
	v_add_f32_e32 v149, v45, v141
	v_mul_f32_e32 v148, 0xbfb8aa3b, v148
	v_mul_f32_e32 v149, 0xbfb8aa3b, v149
	v_exp_f32_e32 v148, v148
	v_exp_f32_e32 v149, v149
	v_add_f32_e32 v148, 1.0, v148
	v_add_f32_e32 v149, 1.0, v149
	v_rcp_f32_e32 v148, v148
	v_rcp_f32_e32 v149, v149
	s_nop 0
	v_cvt_pk_bf16_f32 v185, v148, v149
	v_add_f32_e32 v148, v38, v134
	v_add_f32_e32 v149, v39, v135
	v_mul_f32_e32 v148, 0xbfb8aa3b, v148
	v_mul_f32_e32 v149, 0xbfb8aa3b, v149
	v_exp_f32_e32 v148, v148
	v_exp_f32_e32 v149, v149
	global_store_dwordx4 v[146:147], v[182:185], off offset:2048
	v_add_f32_e32 v148, 1.0, v148
	v_add_f32_e32 v149, 1.0, v149
	v_rcp_f32_e32 v148, v148
	v_rcp_f32_e32 v149, v149
	s_nop 0
	v_cvt_pk_bf16_f32 v182, v148, v149
	v_add_f32_e32 v148, v40, v136
	v_add_f32_e32 v149, v41, v137
	v_mul_f32_e32 v148, 0xbfb8aa3b, v148
	v_mul_f32_e32 v149, 0xbfb8aa3b, v149
	v_exp_f32_e32 v148, v148
	v_exp_f32_e32 v149, v149
	v_add_f32_e32 v148, 1.0, v148
	v_add_f32_e32 v149, 1.0, v149
	v_rcp_f32_e32 v148, v148
	v_rcp_f32_e32 v149, v149
	s_nop 0
	v_cvt_pk_bf16_f32 v183, v148, v149
	v_add_f32_e32 v148, v34, v130
	v_add_f32_e32 v149, v35, v131
	v_mul_f32_e32 v148, 0xbfb8aa3b, v148
	v_mul_f32_e32 v149, 0xbfb8aa3b, v149
	v_exp_f32_e32 v148, v148
	v_exp_f32_e32 v149, v149
	v_add_f32_e32 v148, 1.0, v148
	v_add_f32_e32 v149, 1.0, v149
	v_rcp_f32_e32 v148, v148
	v_rcp_f32_e32 v149, v149
	s_nop 0
	v_cvt_pk_bf16_f32 v184, v148, v149
	v_add_f32_e32 v148, v36, v132
	v_add_f32_e32 v149, v37, v133
	v_mul_f32_e32 v148, 0xbfb8aa3b, v148
	v_mul_f32_e32 v149, 0xbfb8aa3b, v149
	v_exp_f32_e32 v148, v148
	v_exp_f32_e32 v149, v149
	v_add_f32_e32 v148, 1.0, v148
	v_add_f32_e32 v149, 1.0, v149
	v_rcp_f32_e32 v148, v148
	v_rcp_f32_e32 v149, v149
	s_nop 0
	v_cvt_pk_bf16_f32 v185, v148, v149
	global_store_dwordx4 v[146:147], v[182:185], off offset:3072
	v_add_f32_e32 v146, v30, v142
	v_add_f32_e32 v147, v31, v143
	v_mul_f32_e32 v146, 0xbfb8aa3b, v146
	v_mul_f32_e32 v147, 0xbfb8aa3b, v147
	v_exp_f32_e32 v146, v146
	v_exp_f32_e32 v147, v147
	v_add_f32_e32 v148, v22, v134
	v_add_f32_e32 v149, v23, v135
	v_add_f32_e32 v146, 1.0, v146
	v_add_f32_e32 v147, 1.0, v147
	v_rcp_f32_e32 v146, v146
	v_rcp_f32_e32 v147, v147
	v_mul_f32_e32 v148, 0xbfb8aa3b, v148
	v_mul_f32_e32 v149, 0xbfb8aa3b, v149
	v_exp_f32_e32 v148, v148
	v_cvt_pk_bf16_f32 v182, v146, v147
	v_add_f32_e32 v146, v32, v144
	v_add_f32_e32 v147, v33, v145
	v_mul_f32_e32 v146, 0xbfb8aa3b, v146
	v_mul_f32_e32 v147, 0xbfb8aa3b, v147
	v_exp_f32_e32 v146, v146
	v_exp_f32_e32 v147, v147
	v_exp_f32_e32 v149, v149
	v_add_f32_e32 v148, 1.0, v148
	v_add_f32_e32 v146, 1.0, v146
	v_add_f32_e32 v147, 1.0, v147
	v_rcp_f32_e32 v146, v146
	v_rcp_f32_e32 v147, v147
	v_add_f32_e32 v149, 1.0, v149
	v_rcp_f32_e32 v148, v148
	v_rcp_f32_e32 v149, v149
	v_cvt_pk_bf16_f32 v183, v146, v147
	v_add_f32_e32 v146, v26, v138
	v_add_f32_e32 v147, v27, v139
	v_mul_f32_e32 v146, 0xbfb8aa3b, v146
	v_mul_f32_e32 v147, 0xbfb8aa3b, v147
	v_exp_f32_e32 v146, v146
	v_exp_f32_e32 v147, v147
	v_add_f32_e32 v142, v14, v142
	v_add_f32_e32 v143, v15, v143
	v_add_f32_e32 v146, 1.0, v146
	v_add_f32_e32 v147, 1.0, v147
	v_rcp_f32_e32 v146, v146
	v_rcp_f32_e32 v147, v147
	v_add_f32_e32 v134, v6, v134
	v_add_f32_e32 v135, v7, v135
	v_mul_f32_e32 v142, 0xbfb8aa3b, v142
	v_cvt_pk_bf16_f32 v184, v146, v147
	v_add_f32_e32 v146, v28, v140
	v_add_f32_e32 v147, v29, v141
	v_mul_f32_e32 v146, 0xbfb8aa3b, v146
	v_mul_f32_e32 v147, 0xbfb8aa3b, v147
	v_exp_f32_e32 v146, v146
	v_exp_f32_e32 v147, v147
	v_mul_f32_e32 v143, 0xbfb8aa3b, v143
	v_mul_f32_e32 v134, 0xbfb8aa3b, v134
	v_add_f32_e32 v146, 1.0, v146
	v_add_f32_e32 v147, 1.0, v147
	v_rcp_f32_e32 v146, v146
	v_rcp_f32_e32 v147, v147
	v_mul_f32_e32 v135, 0xbfb8aa3b, v135
	v_exp_f32_e32 v142, v142
	v_exp_f32_e32 v143, v143
	v_cvt_pk_bf16_f32 v185, v146, v147
	v_add_co_u32_e32 v146, vcc, s14, v176
	v_exp_f32_e32 v134, v134
	s_nop 0
	v_addc_co_u32_e32 v147, vcc, 0, v177, vcc
	global_store_dwordx4 v[146:147], v[182:185], off
	v_exp_f32_e32 v135, v135
	v_add_f32_e32 v142, 1.0, v142
	v_cvt_pk_bf16_f32 v182, v148, v149
	v_add_f32_e32 v148, v24, v136
	v_add_f32_e32 v149, v25, v137
	v_mul_f32_e32 v148, 0xbfb8aa3b, v148
	v_mul_f32_e32 v149, 0xbfb8aa3b, v149
	v_exp_f32_e32 v148, v148
	v_exp_f32_e32 v149, v149
	v_add_f32_e32 v143, 1.0, v143
	v_add_f32_e32 v134, 1.0, v134
	v_add_f32_e32 v148, 1.0, v148
	v_add_f32_e32 v149, 1.0, v149
	v_add_f32_e32 v135, 1.0, v135
	v_rcp_f32_e32 v148, v148
	v_rcp_f32_e32 v149, v149
	v_rcp_f32_e32 v142, v142
	v_rcp_f32_e32 v143, v143
	v_rcp_f32_e32 v134, v134
	v_rcp_f32_e32 v135, v135
	v_cvt_pk_bf16_f32 v183, v148, v149
	v_add_f32_e32 v148, v18, v130
	v_add_f32_e32 v149, v19, v131
	v_cvt_pk_bf16_f32 v142, v142, v143
	v_add_f32_e32 v143, v16, v144
	v_add_f32_e32 v144, v17, v145
	v_add_f32_e32 v138, v10, v138
	v_add_f32_e32 v139, v11, v139
	v_cvt_pk_bf16_f32 v134, v134, v135
	v_add_f32_e32 v135, v8, v136
	v_add_f32_e32 v136, v9, v137
	v_add_f32_e32 v130, v2, v130
	v_add_f32_e32 v131, v3, v131
	v_mul_f32_e32 v148, 0xbfb8aa3b, v148
	v_mul_f32_e32 v149, 0xbfb8aa3b, v149
	v_mul_f32_e32 v143, 0xbfb8aa3b, v143
	v_mul_f32_e32 v144, 0xbfb8aa3b, v144
	v_mul_f32_e32 v138, 0xbfb8aa3b, v138
	v_mul_f32_e32 v139, 0xbfb8aa3b, v139
	v_mul_f32_e32 v135, 0xbfb8aa3b, v135
	v_mul_f32_e32 v136, 0xbfb8aa3b, v136
	v_mul_f32_e32 v130, 0xbfb8aa3b, v130
	v_mul_f32_e32 v131, 0xbfb8aa3b, v131
	v_exp_f32_e32 v148, v148
	v_exp_f32_e32 v149, v149
	v_exp_f32_e32 v143, v143
	v_exp_f32_e32 v144, v144
	v_exp_f32_e32 v138, v138
	v_exp_f32_e32 v139, v139
	v_exp_f32_e32 v135, v135
	v_exp_f32_e32 v136, v136
	v_exp_f32_e32 v130, v130
	v_exp_f32_e32 v131, v131
	v_add_f32_e32 v148, 1.0, v148
	v_add_f32_e32 v149, 1.0, v149
	v_add_f32_e32 v143, 1.0, v143
	v_add_f32_e32 v144, 1.0, v144
	v_add_f32_e32 v138, 1.0, v138
	v_add_f32_e32 v139, 1.0, v139
	v_add_f32_e32 v135, 1.0, v135
	v_add_f32_e32 v136, 1.0, v136
	v_add_f32_e32 v130, 1.0, v130
	v_add_f32_e32 v131, 1.0, v131
	v_rcp_f32_e32 v148, v148
	v_rcp_f32_e32 v149, v149
	v_rcp_f32_e32 v143, v143
	v_rcp_f32_e32 v144, v144
	v_rcp_f32_e32 v138, v138
	v_rcp_f32_e32 v139, v139
	v_rcp_f32_e32 v135, v135
	v_rcp_f32_e32 v136, v136
	v_rcp_f32_e32 v130, v130
	v_rcp_f32_e32 v131, v131
	v_cvt_pk_bf16_f32 v184, v148, v149
	v_add_f32_e32 v148, v20, v132
	v_add_f32_e32 v149, v21, v133
	v_cvt_pk_bf16_f32 v143, v143, v144
	v_cvt_pk_bf16_f32 v144, v138, v139
	v_add_f32_e32 v138, v12, v140
	v_add_f32_e32 v139, v13, v141
	v_cvt_pk_bf16_f32 v135, v135, v136
	v_cvt_pk_bf16_f32 v136, v130, v131
	v_add_f32_e32 v130, v4, v132
	v_add_f32_e32 v131, v5, v133
	v_mul_f32_e32 v148, 0xbfb8aa3b, v148
	v_mul_f32_e32 v149, 0xbfb8aa3b, v149
	v_mul_f32_e32 v138, 0xbfb8aa3b, v138
	v_mul_f32_e32 v139, 0xbfb8aa3b, v139
	v_mul_f32_e32 v130, 0xbfb8aa3b, v130
	v_mul_f32_e32 v131, 0xbfb8aa3b, v131
	v_exp_f32_e32 v148, v148
	v_exp_f32_e32 v149, v149
	v_exp_f32_e32 v138, v138
	v_exp_f32_e32 v139, v139
	v_exp_f32_e32 v130, v130
	v_exp_f32_e32 v131, v131
	v_add_f32_e32 v148, 1.0, v148
	v_add_f32_e32 v149, 1.0, v149
	v_add_f32_e32 v138, 1.0, v138
	v_add_f32_e32 v139, 1.0, v139
	v_add_f32_e32 v130, 1.0, v130
	v_add_f32_e32 v131, 1.0, v131
	v_rcp_f32_e32 v148, v148
	v_rcp_f32_e32 v149, v149
	v_rcp_f32_e32 v138, v138
	v_rcp_f32_e32 v139, v139
	v_rcp_f32_e32 v130, v130
	v_rcp_f32_e32 v131, v131
	v_cvt_pk_bf16_f32 v185, v148, v149
	v_cvt_pk_bf16_f32 v145, v138, v139
	global_store_dwordx4 v[146:147], v[182:185], off offset:1024
	v_cvt_pk_bf16_f32 v137, v130, v131
	global_store_dwordx4 v[146:147], v[142:145], off offset:2048
	global_store_dwordx4 v[146:147], v[134:137], off offset:3072
